# phase0: weight-conversion items moved off the 96 workgroups that compute the adaLN modulation (static rebalancing)
# baseline (speedup 1.0000x reference)
.LBB0_35:
	s_load_dwordx2 s[10:11], s[16:17], 0x40
	s_lshl_b32 s4, s2, 3
	v_writelane_b32 v255, s4, 1
	s_cmpk_lg_i32 s33, 0x100
	s_cbranch_scc1 .Lp0bal_a
	s_sub_i32 s4, s4, 768
	s_cmp_lt_i32 s2, 96
	s_cselect_b32 s4, 0x100000, s4
.Lp0bal_a:
	v_add_u32_e32 v6, s4, v163
	s_movk_i32 s4, 0x810
	v_lshl_add_u32 v26, v163, 14, 0
	s_lshl_b32 s23, s33, 3
	s_cmpk_lg_i32 s33, 0x100
	s_cbranch_scc1 .Lp0bal_b
	s_sub_i32 s23, s23, 768
.Lp0bal_b:
	v_cmp_gt_i32_e32 vcc, s4, v6
	v_and_b32_e32 v7, 31, v140
	v_lshrrev_b32_e32 v24, 5, v162
	v_lshrrev_b32_e32 v25, 3, v162
	v_lshlrev_b32_e32 v27, 3, v162
	s_and_saveexec_b64 s[4:5], vcc
	s_cbranch_execz .LBB0_272
	s_waitcnt lgkmcnt(0)
	s_add_u32 s6, s14, 0x12400000
	s_addc_u32 s7, s15, 0
	s_add_u32 s12, s14, 0x10000000
	v_and_b32_e32 v2, 56, v27
	s_addc_u32 s13, s15, 0
	v_lshl_add_u32 v4, v7, 2, v26
	v_mul_u32_u24_e32 v8, 0x84, v24
	v_mul_u32_u24_e32 v3, 0x84, v2
	s_add_u32 s18, s14, 0x10500000
	v_lshlrev_b32_e32 v9, 2, v25
	s_addc_u32 s19, s15, 0
	v_mov_b32_e32 v5, 0
	v_add3_u32 v3, v26, v3, v9
	v_or_b32_e32 v9, 8, v25
	v_or_b32_e32 v28, 16, v25
	v_or_b32_e32 v29, 24, v25
	v_bitop3_b32 v30, v25, 15, 24 bitop3:0xc8
	s_mov_b64 s[20:21], 0
	s_mov_b32 s48, 0xfe03f81
	s_movk_i32 s49, 0xff7f
	s_movk_i32 s50, 0x4f
	s_movk_i32 s51, 0x2a10
	s_mov_b32 s52, 0xa840
	v_add_u32_e32 v31, v4, v8
	s_movk_i32 s53, 0x2ff
	s_movk_i32 s54, 0x4ff
	s_movk_i32 s55, 0x7ff
	s_movk_i32 s56, 0x9ff
	s_movk_i32 s57, 0xdff
	s_movk_i32 s58, 0xfff
	s_movk_i32 s59, 0x15ff
	s_movk_i32 s60, 0x160f
	s_movk_i32 s61, 0x60
	s_movk_i32 s62, 0x180f
	s_movk_i32 s63, 0x1a0f
	s_mov_b32 s64, 0x7fffff00
	s_movk_i32 s65, 0x80f
	v_mov_b32_e32 v8, v6
	s_branch .LBB0_38
